# grid barrier: XCD leaders also poll the cross-XCD arrival counter instead of the generation word
# baseline (speedup 1.0000x reference)
; __device__ __forceinline__ unsigned xb_ld(unsigned* p)              { return __hip_atomic_load(p, __ATOMIC_RELAXED, __HIP_MEMORY_SCOPE_AGENT); }
; __device__ __forceinline__ unsigned xb_add(unsigned* p, unsigned v) { return __hip_atomic_fetch_add(p, v, __ATOMIC_RELAXED, __HIP_MEMORY_SCOPE_AGENT); }
; #define XB_SPIN(cond, bar) do { unsigned _sp = 0; while (cond) { __builtin_amdgcn_s_sleep(1); \
;     if ((++_sp & 255u) == 0u) { if (xb_ld(&(bar)[XB_TMO])) break; if (_sp > XB_SPIN_CAP) { atomicAdd(&(bar)[XB_TMO], 1u); break; } } } } while (0)
; __device__ __forceinline__ void xcd_barrier(const XcdBarrier& b) {
;     ...
;             const unsigned og = xb_add(&bar[XB_TOP], 1u);
;             const unsigned tg = og / nx;
;             if (og + 1u == (tg + 1u) * nx) xb_add(&bar[XB_TOPGEN], 1u);
;             else XB_SPIN(xb_ld(&bar[XB_TOPGEN]) == tg, bar);
.LBB0_527:
	s_or_b64 exec, exec, s[6:7]
	s_waitcnt vmcnt(0)
	v_readfirstlane_b32 s4, v5
	v_sub_u32_e32 v6, 0, v4
	s_mov_b64 s[6:7], -1
	v_add_u32_e32 v5, s4, v2
	v_cvt_f32_u32_e32 v2, v4
	v_readlane_b32 s4, v253, 48
	v_readlane_b32 s5, v253, 49
	v_rcp_iflag_f32_e32 v2, v2
	s_nop 0
	v_mul_f32_e32 v2, 0x4f7ffffe, v2
	v_cvt_u32_f32_e32 v2, v2
	v_mul_lo_u32 v6, v6, v2
	v_mul_hi_u32 v6, v2, v6
	v_add_u32_e32 v2, v2, v6
	v_mul_hi_u32 v2, v5, v2
	v_mul_lo_u32 v6, v2, v4
	v_sub_u32_e32 v6, v5, v6
	v_cmp_ge_u32_e32 vcc, v6, v4
	v_add_u32_e32 v7, 1, v2
	v_add_u32_e32 v5, 1, v5
	v_cndmask_b32_e32 v2, v2, v7, vcc
	v_sub_u32_e32 v7, v6, v4
	v_cndmask_b32_e32 v6, v6, v7, vcc
	v_cmp_ge_u32_e32 vcc, v6, v4
	v_add_u32_e32 v6, 1, v2
	s_nop 0
	v_cndmask_b32_e32 v2, v2, v6, vcc
	v_mul_lo_u32 v6, v4, v2
	v_add_u32_e32 v4, v6, v4
	v_mov_b32_e32 v8, v4
	v_cmp_ne_u32_e32 vcc, v5, v4
	v_mov_b64_e32 v[4:5], s[4:5]
	s_and_saveexec_b64 s[4:5], vcc
	s_cbranch_execz .LBB0_539
	v_readlane_b32 s6, v253, 46
	v_readlane_b32 s7, v253, 47
	s_mov_b64 s[8:9], 0
	s_nop 3
	global_load_dword v4, v3, s[6:7] sc1
	s_waitcnt vmcnt(0)
	v_cmp_lt_u32_e32 vcc, v4, v8
	s_and_saveexec_b64 s[6:7], vcc
	s_cbranch_execz .LBB0_538
	s_mov_b32 s18, 1
	s_branch .LBB0_531

; __device__ __forceinline__ unsigned xb_ld(unsigned* p)              { return __hip_atomic_load(p, __ATOMIC_RELAXED, __HIP_MEMORY_SCOPE_AGENT); }
; #define XB_SPIN(cond, bar) do { unsigned _sp = 0; while (cond) { __builtin_amdgcn_s_sleep(1); \
;     if ((++_sp & 255u) == 0u) { if (xb_ld(&(bar)[XB_TMO])) break; if (_sp > XB_SPIN_CAP) { atomicAdd(&(bar)[XB_TMO], 1u); break; } } } } while (0)
; __device__ __forceinline__ void xcd_barrier(const XcdBarrier& b) {
;     ...
;             else XB_SPIN(xb_ld(&bar[XB_TOPGEN]) == tg, bar);
.LBB0_535:
	v_readlane_b32 s12, v253, 46
	v_readlane_b32 s13, v253, 47
	s_add_i32 s18, s18, 1
	s_mov_b64 s[14:15], -1
	s_nop 2
	global_load_dword v4, v3, s[12:13] sc1
	s_waitcnt vmcnt(0)
	v_cmp_ge_u32_e32 vcc, v4, v8
	s_orn2_b64 s[12:13], vcc, exec
	s_branch .LBB0_530
